# prologue's layer-1..3 W2 tail conversions (12192 items) moved into the mixer phase slack of layers 0..2 (192 non-scan WGs); on top of nt4
# speedup vs baseline: 1.0172x; 1.0172x over previous
; #define CV_MAP(g_, l_, it_) do { (l_) = lfix; \
;         if (MODE == 2) (it_) = CV_S0 + base + (g_); \
;         else if (MODE == 1) (it_) = cv_ritem(g_); \
;         else if ((g_) < CV_NR) (it_) = cv_ritem(g_); \
;         else { const int q_ = ((g_) - CV_NR) / CV_RPRO; (l_) = 1 + q_; (it_) = cv_ritem(CV_DEFER + ((g_) - CV_NR) - q_ * CV_RPRO); } } while (0)
; template <int MODE>
; __device__ __forceinline__ void cv_jobs(const Frame& F, const Args& a, int lfix, int base, int njobs, int w, int nw) {
;     ...
;     for (int g = w; g < njobs; g += 2 * nw) {
;         const int g1 = g + nw; int l, it, l1, it1; CV_MAP(g, l, it); CV_MAP(g1, l1, it1);
; __device__ __forceinline__ void p0_prologue(const Frame& F0, const Args& a0) {
;     const Frame F = relaunder(F0); const Args a = relaunder_args(a0);
;     unsigned char* ws = a.ws;
;     for (int rep = 0; rep < REP_PT; ++rep) cv_jobs<0>(F, a, 0, 0, CV_NR + (DEPTH - 1) * CV_RPRO, F.vcu * NWAVES + F.wave, F.G * NWAVES);
.LBB0_7:
	s_or_b64 exec, exec, s[0:1]
	v_writelane_b32 v221, s40, 34
	s_lshr_b32 s95, s4, 6
	s_mov_b64 s[4:5], s[64:65]
	v_writelane_b32 v221, s41, 35
	v_writelane_b32 v221, s42, 36
	v_writelane_b32 v221, s43, 37
	v_writelane_b32 v221, s44, 38
	v_writelane_b32 v221, s45, 39
	v_writelane_b32 v221, s46, 40
	v_writelane_b32 v221, s47, 41
	s_cmp_lt_i32 s64, 1
	v_writelane_b32 v221, s4, 42
	s_cselect_b64 s[0:1], -1, 0
	s_cmp_gt_i32 s65, 0
	v_writelane_b32 v221, s5, 43
	s_cselect_b64 s[2:3], -1, 0
	v_writelane_b32 v221, s6, 44
	s_and_b64 s[0:1], s[0:1], s[2:3]
	v_writelane_b32 v221, s7, 45
	s_andn2_b64 vcc, exec, s[0:1]
	v_writelane_b32 v221, s38, 46
	s_nop 1
	v_writelane_b32 v221, s39, 47
	s_cbranch_vccnz .LBB0_110
	s_mov_b32 s2, s94
	s_mov_b32 s21, s95
	s_mov_b32 s10, s92
	s_mov_b32 s14, s93
	v_readlane_b32 s48, v221, 0
	v_mbcnt_lo_u32_b32 v67, -1, 0
	v_mbcnt_hi_u32_b32 v67, -1, v67
	v_readlane_b32 s49, v221, 1
	s_mov_b64 s[2:3], s[48:49]
	v_readlane_b32 s50, v221, 2
	v_readlane_b32 s51, v221, 3
	v_readlane_b32 s52, v221, 4
	v_readlane_b32 s53, v221, 5
	s_mov_b64 s[30:31], s[50:51]
	s_mov_b64 s[2:3], s[52:53]
	v_readlane_b32 s54, v221, 6
	v_readlane_b32 s55, v221, 7
	v_readlane_b32 s56, v221, 8
	v_readlane_b32 s57, v221, 9
	v_readlane_b32 s58, v221, 10
	v_readlane_b32 s59, v221, 11
	v_readlane_b32 s60, v221, 12
	v_readlane_b32 s61, v221, 13
	s_mov_b64 s[34:35], s[54:55]
	s_mov_b64 s[18:19], s[56:57]
	s_mov_b64 s[16:17], s[58:59]
	s_mov_b64 s[2:3], s[60:61]
	v_readlane_b32 s64, v221, 16
	v_readlane_b32 s62, v221, 14
	v_readlane_b32 s63, v221, 15
	v_readlane_b32 s65, v221, 17
	s_mov_b64 s[2:3], s[62:63]
	s_mov_b64 s[4:5], s[64:65]
	v_readlane_b32 s66, v221, 18
	v_readlane_b32 s67, v221, 19
	s_mov_b64 s[4:5], s[66:67]
	v_readlane_b32 s68, v221, 20
	v_readlane_b32 s69, v221, 21
	s_mov_b64 s[4:5], s[68:69]
	v_readlane_b32 s70, v221, 22
	v_readlane_b32 s71, v221, 23
	s_mov_b64 s[4:5], s[70:71]
	v_readlane_b32 s72, v221, 24
	v_readlane_b32 s73, v221, 25
	s_mov_b64 s[4:5], s[72:73]
	v_readlane_b32 s74, v221, 26
	v_readlane_b32 s75, v221, 27
	v_readlane_b32 s76, v221, 28
	v_readlane_b32 s77, v221, 29
	s_mov_b64 s[4:5], s[74:75]
	s_mov_b64 s[6:7], s[76:77]
	v_readlane_b32 s78, v221, 30
	v_readlane_b32 s79, v221, 31
	s_mov_b64 s[6:7], s[78:79]
	s_mov_b64 s[8:9], s[40:41]
	s_mov_b64 s[12:13], s[42:43]
	s_lshl_b32 s11, s14, 3
	s_add_i32 s11, s11, s21
	s_mov_b64 s[12:13], s[44:45]
	s_mov_b64 s[68:69], s[46:47]
	s_cmpk_gt_i32 s11, 0x3fdf
	v_lshlrev_b32_e32 v68, 2, v67
	s_cbranch_scc1 .LBB0_70
	s_lshl_b32 s12, s21, 14
	s_lshl_b32 s15, s10, 3
	s_add_i32 s12, s12, 0
	s_lshl_b32 s22, s10, 4
	s_add_u32 s23, s68, 0x10000000
	s_addc_u32 s24, s69, 0
	v_lshlrev_b32_e32 v1, 3, v67
	v_ashrrev_i32_e32 v69, 3, v67
	v_and_b32_e32 v66, 56, v1
	s_add_u32 s25, s68, 0x8000000
	v_mul_u32_u24_e32 v1, 0x84, v66
	v_lshlrev_b32_e32 v2, 2, v69
	s_addc_u32 s26, s69, 0
	v_add_u32_e32 v72, 8, v69
	v_add3_u32 v75, s12, v1, v2
	v_lshlrev_b32_e32 v1, 1, v69
	s_add_u32 s27, s68, 0x6000000
	v_add_u32_e32 v73, 16, v69
	v_and_b32_e32 v76, 62, v1
	v_lshlrev_b32_e32 v1, 1, v72
	s_addc_u32 s28, s69, 0
	v_and_b32_e32 v0, 28, v68
	v_add_u32_e32 v74, 24, v69
	v_and_b32_e32 v77, 62, v1
	v_lshlrev_b32_e32 v1, 1, v73
	s_add_u32 s29, s68, 0x400000
	v_lshl_add_u32 v70, v0, 2, s12
	s_movk_i32 s13, 0x84
	v_and_b32_e32 v78, 62, v1
	v_lshlrev_b32_e32 v1, 1, v74
	s_addc_u32 s33, s69, 0
	s_add_i32 s12, s11, s15
	s_mov_b32 s71, 0
	v_mov_b32_e32 v65, 0
	v_mul_lo_u32 v71, v69, s13
	v_and_b32_e32 v79, 62, v1
	s_add_i32 s36, s11, 0xc020
	s_add_i32 s37, s15, 0xfffff020
	s_add_i32 s38, s12, 0xffffc020
	s_add_i32 s39, s15, 0xe60
	s_mov_b32 s40, 0x10000
	s_mov_b32 s41, 0x20000
	s_mov_b32 s42, 0x30000
	s_mov_b32 s43, 0x40000
	s_mov_b32 s44, 0x50000
	s_mov_b32 s45, 0x60000
	s_mov_b64 s[72:73], 0x70000
	s_mov_b64 s[74:75], 0x1c0000
	s_movk_i32 s46, 0x5880
	s_mov_b64 s[76:77], 0x40000
	s_movk_i32 s47, 0x500
	v_lshlrev_b32_e32 v64, 2, v0
	s_branch .LBB0_11
.LBB0_10:
	s_add_i32 s11, s11, s22
	s_add_i32 s36, s36, s22
	s_add_i32 s38, s38, s22
	s_cmpk_lt_i32 s11, 0x3fe0
	s_cbranch_scc0 .LBB0_70

; #define CV_MAP(g_, l_, it_) do { (l_) = lfix; \
;         if (MODE == 2) (it_) = CV_S0 + base + (g_); \
;         else if (MODE == 1) (it_) = cv_ritem(g_); \
;         else if ((g_) < CV_NR) (it_) = cv_ritem(g_); \
;         else { const int q_ = ((g_) - CV_NR) / CV_RPRO; (l_) = 1 + q_; (it_) = cv_ritem(CV_DEFER + ((g_) - CV_NR) - q_ * CV_RPRO); } } while (0)
; __device__ __forceinline__ void p0_item_load(const float* W, int N, int item, int lane, f32x4 (&wv)[8]) {
;     const int nblk = N / 32, kb = item / nblk, nb = item % nblk, k0 = 64 * kb, n0 = 32 * nb;
; #pragma unroll
;     for (int i = 0; i < 8; ++i) wv[i] = *(const f32x4*)(W + (size_t)(k0 + 8 * i + (lane >> 3)) * N + n0 + 4 * (lane & 7));
; }
; template <int MODE>
; __device__ __forceinline__ void cv_jobs(const Frame& F, const Args& a, int lfix, int base, int njobs, int w, int nw) {
;     ...
;     for (int g = w; g < njobs; g += 2 * nw) {
;         const int g1 = g + nw; int l, it, l1, it1; CV_MAP(g, l, it); CV_MAP(g1, l1, it1);
;         cv_load(a, l, it, F.lane, sa);
;         if (g1 < njobs) cv_load(a, l1, it1, F.lane, sb);
.LBB0_31:
	s_waitcnt vmcnt(0)
	global_load_dwordx4 v[60:63], v[60:61], off nt
	s_cmpk_lt_i32 s51, 0x3fe0
	s_cselect_b64 s[82:83], -1, 0
	s_cmpk_gt_i32 s51, 0x3fdf
	s_cbranch_scc1 .LBB0_47
	s_cmpk_gt_i32 s48, 0x161f
	s_mov_b64 s[84:85], -1
	s_cbranch_scc0 .LBB0_42
	s_cmpk_gt_u32 s48, 0x1e1f
	s_cbranch_scc0 .LBB0_39
	s_lshl_b64 s[84:85], s[78:79], 26
	s_cmpk_gt_u32 s48, 0x3e1f
	s_mov_b64 s[86:87], -1
	s_cbranch_scc0 .LBB0_36
	s_add_u32 s51, s8, s84
	s_addc_u32 s53, s9, s85
	s_add_i32 s52, s48, 0xffffc1e0
	s_and_b32 s54, s52, 0xffffffc0
	s_lshl_b32 s52, s52, 7
	v_add_u32_e32 v2, s54, v69
	s_and_b32 s52, s52, 0x1f80
	s_add_u32 s52, s51, s52
	v_add_u32_e32 v10, 24, v2
	s_addc_u32 s53, s53, 0
	v_ashrrev_i32_e32 v11, 31, v10
	v_lshl_add_u64 v[6:7], s[52:53], 0, v[64:65]
	v_lshlrev_b64 v[10:11], 13, v[10:11]
	v_lshl_add_u64 v[12:13], v[6:7], 0, v[10:11]
	v_add_u32_e32 v10, 32, v2
	v_ashrrev_i32_e32 v11, 31, v10
	v_lshlrev_b64 v[10:11], 13, v[10:11]
	v_lshl_add_u64 v[16:17], v[6:7], 0, v[10:11]
	v_add_u32_e32 v10, 40, v2
	v_ashrrev_i32_e32 v11, 31, v10
	v_ashrrev_i32_e32 v3, 31, v2
	v_lshlrev_b64 v[10:11], 13, v[10:11]
	v_lshlrev_b64 v[0:1], 13, v[2:3]
	v_add_u32_e32 v4, 8, v2
	v_add_u32_e32 v8, 16, v2
	v_lshl_add_u64 v[20:21], v[6:7], 0, v[10:11]
	v_add_u32_e32 v10, 48, v2
	v_add_u32_e32 v2, 56, v2
	v_ashrrev_i32_e32 v5, 31, v4
	v_ashrrev_i32_e32 v9, 31, v8
	v_ashrrev_i32_e32 v11, 31, v10
	v_ashrrev_i32_e32 v3, 31, v2
	v_lshlrev_b64 v[4:5], 13, v[4:5]
	v_lshlrev_b64 v[8:9], 13, v[8:9]
	v_lshlrev_b64 v[10:11], 13, v[10:11]
	v_lshlrev_b64 v[2:3], 13, v[2:3]
	v_lshl_add_u64 v[0:1], v[6:7], 0, v[0:1]
	v_lshl_add_u64 v[4:5], v[6:7], 0, v[4:5]
	v_lshl_add_u64 v[8:9], v[6:7], 0, v[8:9]
	v_lshl_add_u64 v[24:25], v[6:7], 0, v[10:11]
	v_lshl_add_u64 v[28:29], v[6:7], 0, v[2:3]
	s_mov_b64 s[86:87], 0

; #define CV_MAP(g_, l_, it_) do { (l_) = lfix; \
;         if (MODE == 2) (it_) = CV_S0 + base + (g_); \
;         else if (MODE == 1) (it_) = cv_ritem(g_); \
;         else if ((g_) < CV_NR) (it_) = cv_ritem(g_); \
;         else { const int q_ = ((g_) - CV_NR) / CV_RPRO; (l_) = 1 + q_; (it_) = cv_ritem(CV_DEFER + ((g_) - CV_NR) - q_ * CV_RPRO); } } while (0)
; template <int MODE>
; __device__ __forceinline__ void cv_jobs(const Frame& F, const Args& a, int lfix, int base, int njobs, int w, int nw) {
;     ...
;     for (int g = w; g < njobs; g += 2 * nw) {
;         const int g1 = g + nw; int l, it, l1, it1; CV_MAP(g, l, it); CV_MAP(g1, l1, it1);
;         cv_load(a, l, it, F.lane, sa);
;         if (g1 < njobs) cv_load(a, l1, it1, F.lane, sb);
;         cv_store(a, sa, scr, l, it, F.lane);
;         if (g1 < njobs) cv_store(a, sb, scr, l1, it1, F.lane);
;     }
; __global__ void __launch_bounds__(NTHREADS, 2) fwd(Args args) {
;     ...
;             for (int r2 = 0; r2 < REP_ATTN; ++r2) {
;                 if (F.bx >= 64 && F.bx < 124) attn_phase(F, args, l, F.bx - 64, 1, 1, 512, 512 + (F.bx - 64), last);
;                 else if (F.bx >= 124) attn_phase(F, args, l, 60 + (F.bx - 124), 132, 4, 512, F.bx >= 252 ? 572 + (F.bx - 252) : -1, last); }
;             if (rep == 0 && CV_P3 > 0 && F.bx >= 180) { __syncthreads(); cv_deferred<2>(F, args, l, CV_PREP, CV_P3, (F.bx - 180) * NWAVES + F.wave, 76 * NWAVES); }
;             if (rep + 1 < REP_MIX) xcd_barrier(bar); }
.Ltail_entry:
	v_readlane_b32 s98, v220, 18
	v_readlane_b32 s99, v220, 26
	s_nop 1
	s_cmp_lt_u32 s98, 64
	s_cbranch_scc1 .LBB0_687
	s_cmp_gt_u32 s99, 2
	s_cbranch_scc1 .LBB0_687
	s_waitcnt vmcnt(0) lgkmcnt(0)
	s_barrier
	v_writelane_b32 v222, s2, 0
	v_writelane_b32 v222, s3, 1
	v_writelane_b32 v222, s4, 2
	v_writelane_b32 v222, s5, 3
	v_writelane_b32 v222, s6, 4
	v_writelane_b32 v222, s7, 5
	v_writelane_b32 v222, s8, 6
	v_writelane_b32 v222, s9, 7
	v_writelane_b32 v222, s10, 8
	v_writelane_b32 v222, s11, 9
	v_writelane_b32 v222, s12, 10
	v_writelane_b32 v222, s13, 11
	v_writelane_b32 v222, s14, 12
	v_writelane_b32 v222, s15, 13
	v_writelane_b32 v222, s16, 14
	v_writelane_b32 v222, s17, 15
	v_writelane_b32 v222, s18, 16
	v_writelane_b32 v222, s19, 17
	v_writelane_b32 v222, s20, 18
	v_writelane_b32 v222, s21, 19
	v_writelane_b32 v222, s22, 20
	v_writelane_b32 v222, s23, 21
	v_writelane_b32 v222, s24, 22
	v_writelane_b32 v222, s25, 23
	v_writelane_b32 v222, s26, 24
	v_writelane_b32 v222, s27, 25
	v_writelane_b32 v222, s28, 26
	v_writelane_b32 v222, s29, 27
	v_writelane_b32 v222, s30, 28
	v_writelane_b32 v222, s31, 29
	v_writelane_b32 v222, s32, 30
	v_writelane_b32 v222, s33, 31
	v_writelane_b32 v222, s34, 32
	v_writelane_b32 v222, s35, 33
	v_writelane_b32 v222, s36, 34
	v_writelane_b32 v222, s37, 35
	v_writelane_b32 v222, s38, 36
	v_writelane_b32 v222, s39, 37
	v_writelane_b32 v222, s40, 38
	v_writelane_b32 v222, s41, 39
	v_writelane_b32 v222, s42, 40
	v_writelane_b32 v222, s43, 41
	v_writelane_b32 v222, s44, 42
	v_writelane_b32 v222, s45, 43
	v_writelane_b32 v222, s46, 44
	v_writelane_b32 v222, s47, 45
	v_writelane_b32 v222, s48, 46
	v_writelane_b32 v222, s49, 47
	v_writelane_b32 v222, s50, 48
	v_writelane_b32 v222, s51, 49
	v_writelane_b32 v222, s52, 50
	v_writelane_b32 v222, s53, 51
	v_writelane_b32 v222, s54, 52
	v_writelane_b32 v222, s55, 53
	v_writelane_b32 v222, s56, 54
	v_writelane_b32 v222, s57, 55
	v_writelane_b32 v222, s58, 56
	v_writelane_b32 v222, s59, 57
	v_writelane_b32 v222, s60, 58
	v_writelane_b32 v222, s61, 59
	v_writelane_b32 v222, s62, 60
	v_writelane_b32 v222, s63, 61
	v_writelane_b32 v222, s64, 62
	v_writelane_b32 v222, s65, 63
	v_writelane_b32 v223, s66, 0
	v_writelane_b32 v223, s67, 1
	v_writelane_b32 v223, s68, 2
	v_writelane_b32 v223, s69, 3
	v_writelane_b32 v223, s70, 4
	v_writelane_b32 v223, s71, 5
	v_writelane_b32 v223, s72, 6
	v_writelane_b32 v223, s73, 7
	v_writelane_b32 v223, s74, 8
	v_writelane_b32 v223, s75, 9
	v_writelane_b32 v223, s76, 10
	v_writelane_b32 v223, s77, 11
	v_writelane_b32 v223, s78, 12
	v_writelane_b32 v223, s79, 13
	v_writelane_b32 v223, s80, 14
	v_writelane_b32 v223, s81, 15
	v_writelane_b32 v223, s82, 16
	v_writelane_b32 v223, s83, 17
	v_writelane_b32 v223, s84, 18
	v_writelane_b32 v223, s85, 19
	v_writelane_b32 v223, s86, 20
	v_writelane_b32 v223, s87, 21
	v_readlane_b32 s40, v221, 34
	v_readlane_b32 s41, v221, 35
	v_readlane_b32 s42, v221, 36
	v_readlane_b32 s43, v221, 37
	v_readlane_b32 s44, v221, 38
	v_readlane_b32 s45, v221, 39
	v_readlane_b32 s46, v221, 40
	v_readlane_b32 s47, v221, 41
	s_mov_b64 exec, -1
	s_mul_i32 s98, s99, 4064
	s_add_i32 s98, s98, 16352
	s_add_i32 s99, s98, 4064
	v_readlane_b32 s2, v220, 18
	v_readlane_b32 s21, v220, 17
	s_movk_i32 s10, 192
	v_readlane_b32 s14, v220, 18
	s_nop 1
	s_sub_i32 s14, s14, 64
	v_readlane_b32 s48, v221, 0
	v_mbcnt_lo_u32_b32 v67, -1, 0
	v_mbcnt_hi_u32_b32 v67, -1, v67
	v_readlane_b32 s49, v221, 1
	s_mov_b64 s[2:3], s[48:49]
	v_readlane_b32 s50, v221, 2
	v_readlane_b32 s51, v221, 3
	v_readlane_b32 s52, v221, 4
	v_readlane_b32 s53, v221, 5
	s_mov_b64 s[30:31], s[50:51]
	s_mov_b64 s[2:3], s[52:53]
	v_readlane_b32 s54, v221, 6
	v_readlane_b32 s55, v221, 7
	v_readlane_b32 s56, v221, 8
	v_readlane_b32 s57, v221, 9
	v_readlane_b32 s58, v221, 10
	v_readlane_b32 s59, v221, 11
	v_readlane_b32 s60, v221, 12
	v_readlane_b32 s61, v221, 13
	s_mov_b64 s[34:35], s[54:55]
	s_mov_b64 s[18:19], s[56:57]
	s_mov_b64 s[16:17], s[58:59]
	s_mov_b64 s[2:3], s[60:61]
	v_readlane_b32 s64, v221, 16
	v_readlane_b32 s62, v221, 14
	v_readlane_b32 s63, v221, 15
	v_readlane_b32 s65, v221, 17
	s_mov_b64 s[2:3], s[62:63]
	s_mov_b64 s[4:5], s[64:65]
	v_readlane_b32 s66, v221, 18
	v_readlane_b32 s67, v221, 19
	s_mov_b64 s[4:5], s[66:67]
	v_readlane_b32 s68, v221, 20
	v_readlane_b32 s69, v221, 21
	s_mov_b64 s[4:5], s[68:69]
	v_readlane_b32 s70, v221, 22
	v_readlane_b32 s71, v221, 23
	s_mov_b64 s[4:5], s[70:71]
	v_readlane_b32 s72, v221, 24
	v_readlane_b32 s73, v221, 25
	s_mov_b64 s[4:5], s[72:73]
	v_readlane_b32 s74, v221, 26
	v_readlane_b32 s75, v221, 27
	v_readlane_b32 s76, v221, 28
	v_readlane_b32 s77, v221, 29
	s_mov_b64 s[4:5], s[74:75]
	s_mov_b64 s[6:7], s[76:77]
	v_readlane_b32 s78, v221, 30
	v_readlane_b32 s79, v221, 31
	s_mov_b64 s[6:7], s[78:79]
	s_mov_b64 s[8:9], s[40:41]
	s_mov_b64 s[12:13], s[42:43]
	s_lshl_b32 s11, s14, 3
	s_add_i32 s11, s11, s21
	s_add_i32 s11, s11, s98
	s_mov_b64 s[12:13], s[44:45]
	s_mov_b64 s[68:69], s[46:47]
	s_cmp_ge_i32 s11, s99
	v_lshlrev_b32_e32 v68, 2, v67
	s_cbranch_scc1 .Ltail_done
	s_lshl_b32 s12, s21, 14
	s_lshl_b32 s15, s10, 3
	s_add_i32 s12, s12, 0
	s_lshl_b32 s22, s10, 4
	s_add_u32 s23, s68, 0x10000000
	s_addc_u32 s24, s69, 0
	v_lshlrev_b32_e32 v1, 3, v67
	v_ashrrev_i32_e32 v69, 3, v67
	v_and_b32_e32 v66, 56, v1
	s_add_u32 s25, s68, 0x8000000
	v_mul_u32_u24_e32 v1, 0x84, v66
	v_lshlrev_b32_e32 v2, 2, v69
	s_addc_u32 s26, s69, 0
	v_add_u32_e32 v72, 8, v69
	v_add3_u32 v75, s12, v1, v2
	v_lshlrev_b32_e32 v1, 1, v69
	s_add_u32 s27, s68, 0x6000000
	v_add_u32_e32 v73, 16, v69
	v_and_b32_e32 v76, 62, v1
	v_lshlrev_b32_e32 v1, 1, v72
	s_addc_u32 s28, s69, 0
	v_and_b32_e32 v0, 28, v68
	v_add_u32_e32 v74, 24, v69
	v_and_b32_e32 v77, 62, v1
	v_lshlrev_b32_e32 v1, 1, v73
	s_add_u32 s29, s68, 0x400000
	v_lshl_add_u32 v70, v0, 2, s12
	s_movk_i32 s13, 0x84
	v_and_b32_e32 v78, 62, v1
	v_lshlrev_b32_e32 v1, 1, v74
	s_addc_u32 s33, s69, 0
	s_add_i32 s12, s11, s15
	s_mov_b32 s71, 0
	v_mov_b32_e32 v65, 0
	v_mul_lo_u32 v71, v69, s13
	v_and_b32_e32 v79, 62, v1
	s_add_i32 s36, s11, 0xc020
	s_add_i32 s37, s15, 0xfffff020
	s_add_i32 s38, s12, 0xffffc020
	s_add_i32 s39, s15, 0xe60
	s_mov_b32 s40, 0x10000
	s_mov_b32 s41, 0x20000
	s_mov_b32 s42, 0x30000
	s_mov_b32 s43, 0x40000
	s_mov_b32 s44, 0x50000
	s_mov_b32 s45, 0x60000
	s_mov_b64 s[72:73], 0x70000
	s_mov_b64 s[74:75], 0x1c0000
	s_movk_i32 s46, 0x5880
	s_mov_b64 s[76:77], 0x40000
	s_movk_i32 s47, 0x500
	v_lshlrev_b32_e32 v64, 2, v0
	s_branch .Ltl_11
.Ltl_10:
	s_add_i32 s11, s11, s22
	s_add_i32 s36, s36, s22
	s_add_i32 s38, s38, s22
	s_cmp_lt_i32 s11, s99
	s_cbranch_scc0 .Ltail_done

; #define CV_MAP(g_, l_, it_) do { (l_) = lfix; \
;         if (MODE == 2) (it_) = CV_S0 + base + (g_); \
;         else if (MODE == 1) (it_) = cv_ritem(g_); \
;         else if ((g_) < CV_NR) (it_) = cv_ritem(g_); \
;         else { const int q_ = ((g_) - CV_NR) / CV_RPRO; (l_) = 1 + q_; (it_) = cv_ritem(CV_DEFER + ((g_) - CV_NR) - q_ * CV_RPRO); } } while (0)
; template <int MODE>
; __device__ __forceinline__ void cv_jobs(const Frame& F, const Args& a, int lfix, int base, int njobs, int w, int nw) {
;     ...
;     for (int g = w; g < njobs; g += 2 * nw) {
;         const int g1 = g + nw; int l, it, l1, it1; CV_MAP(g, l, it); CV_MAP(g1, l1, it1);
;         cv_load(a, l, it, F.lane, sa);
;         if (g1 < njobs) cv_load(a, l1, it1, F.lane, sb);
.Ltl_31:
	s_waitcnt vmcnt(0)
	global_load_dwordx4 v[60:63], v[60:61], off nt
	s_cmp_lt_i32 s51, s99
	s_cselect_b64 s[82:83], -1, 0
	s_cmp_ge_i32 s51, s99
	s_cbranch_scc1 .Ltl_47
	s_cmpk_gt_i32 s48, 0x161f
	s_mov_b64 s[84:85], -1
	s_cbranch_scc0 .Ltl_42
	s_cmpk_gt_u32 s48, 0x1e1f
	s_cbranch_scc0 .Ltl_39
	s_lshl_b64 s[84:85], s[78:79], 26
	s_cmpk_gt_u32 s48, 0x3e1f
	s_mov_b64 s[86:87], -1
	s_cbranch_scc0 .Ltl_36
	s_add_u32 s51, s8, s84
	s_addc_u32 s53, s9, s85
	s_add_i32 s52, s48, 0xffffc1e0
	s_and_b32 s54, s52, 0xffffffc0
	s_lshl_b32 s52, s52, 7
	v_add_u32_e32 v2, s54, v69
	s_and_b32 s52, s52, 0x1f80
	s_add_u32 s52, s51, s52
	v_add_u32_e32 v10, 24, v2
	s_addc_u32 s53, s53, 0
	v_ashrrev_i32_e32 v11, 31, v10
	v_lshl_add_u64 v[6:7], s[52:53], 0, v[64:65]
	v_lshlrev_b64 v[10:11], 13, v[10:11]
	v_lshl_add_u64 v[12:13], v[6:7], 0, v[10:11]
	v_add_u32_e32 v10, 32, v2
	v_ashrrev_i32_e32 v11, 31, v10
	v_lshlrev_b64 v[10:11], 13, v[10:11]
	v_lshl_add_u64 v[16:17], v[6:7], 0, v[10:11]
	v_add_u32_e32 v10, 40, v2
	v_ashrrev_i32_e32 v11, 31, v10
	v_ashrrev_i32_e32 v3, 31, v2
	v_lshlrev_b64 v[10:11], 13, v[10:11]
	v_lshlrev_b64 v[0:1], 13, v[2:3]
	v_add_u32_e32 v4, 8, v2
	v_add_u32_e32 v8, 16, v2
	v_lshl_add_u64 v[20:21], v[6:7], 0, v[10:11]
	v_add_u32_e32 v10, 48, v2
	v_add_u32_e32 v2, 56, v2
	v_ashrrev_i32_e32 v5, 31, v4
	v_ashrrev_i32_e32 v9, 31, v8
	v_ashrrev_i32_e32 v11, 31, v10
	v_ashrrev_i32_e32 v3, 31, v2
	v_lshlrev_b64 v[4:5], 13, v[4:5]
	v_lshlrev_b64 v[8:9], 13, v[8:9]
	v_lshlrev_b64 v[10:11], 13, v[10:11]
	v_lshlrev_b64 v[2:3], 13, v[2:3]
	v_lshl_add_u64 v[0:1], v[6:7], 0, v[0:1]
	v_lshl_add_u64 v[4:5], v[6:7], 0, v[4:5]
	v_lshl_add_u64 v[8:9], v[6:7], 0, v[8:9]
	v_lshl_add_u64 v[24:25], v[6:7], 0, v[10:11]
	v_lshl_add_u64 v[28:29], v[6:7], 0, v[2:3]
	s_mov_b64 s[86:87], 0

; __global__ void __launch_bounds__(NTHREADS, 2) fwd(Args args) {
;     ...
;             for (int r2 = 0; r2 < REP_ATTN; ++r2) {
;                 if (F.bx >= 64 && F.bx < 124) attn_phase(F, args, l, F.bx - 64, 1, 1, 512, 512 + (F.bx - 64), last);
;                 else if (F.bx >= 124) attn_phase(F, args, l, 60 + (F.bx - 124), 132, 4, 512, F.bx >= 252 ? 572 + (F.bx - 252) : -1, last); }
;             if (rep == 0 && CV_P3 > 0 && F.bx >= 180) { __syncthreads(); cv_deferred<2>(F, args, l, CV_PREP, CV_P3, (F.bx - 180) * NWAVES + F.wave, 76 * NWAVES); }
;             if (rep + 1 < REP_MIX) xcd_barrier(bar); }
.Ltail_done:
	s_nop 0
	v_readlane_b32 s2, v222, 0
	v_readlane_b32 s3, v222, 1
	v_readlane_b32 s4, v222, 2
	v_readlane_b32 s5, v222, 3
	v_readlane_b32 s6, v222, 4
	v_readlane_b32 s7, v222, 5
	v_readlane_b32 s8, v222, 6
	v_readlane_b32 s9, v222, 7
	v_readlane_b32 s10, v222, 8
	v_readlane_b32 s11, v222, 9
	v_readlane_b32 s12, v222, 10
	v_readlane_b32 s13, v222, 11
	v_readlane_b32 s14, v222, 12
	v_readlane_b32 s15, v222, 13
	v_readlane_b32 s16, v222, 14
	v_readlane_b32 s17, v222, 15
	v_readlane_b32 s18, v222, 16
	v_readlane_b32 s19, v222, 17
	v_readlane_b32 s20, v222, 18
	v_readlane_b32 s21, v222, 19
	v_readlane_b32 s22, v222, 20
	v_readlane_b32 s23, v222, 21
	v_readlane_b32 s24, v222, 22
	v_readlane_b32 s25, v222, 23
	v_readlane_b32 s26, v222, 24
	v_readlane_b32 s27, v222, 25
	v_readlane_b32 s28, v222, 26
	v_readlane_b32 s29, v222, 27
	v_readlane_b32 s30, v222, 28
	v_readlane_b32 s31, v222, 29
	v_readlane_b32 s32, v222, 30
	v_readlane_b32 s33, v222, 31
	v_readlane_b32 s34, v222, 32
	v_readlane_b32 s35, v222, 33
	v_readlane_b32 s36, v222, 34
	v_readlane_b32 s37, v222, 35
	v_readlane_b32 s38, v222, 36
	v_readlane_b32 s39, v222, 37
	v_readlane_b32 s40, v222, 38
	v_readlane_b32 s41, v222, 39
	v_readlane_b32 s42, v222, 40
	v_readlane_b32 s43, v222, 41
	v_readlane_b32 s44, v222, 42
	v_readlane_b32 s45, v222, 43
	v_readlane_b32 s46, v222, 44
	v_readlane_b32 s47, v222, 45
	v_readlane_b32 s48, v222, 46
	v_readlane_b32 s49, v222, 47
	v_readlane_b32 s50, v222, 48
	v_readlane_b32 s51, v222, 49
	v_readlane_b32 s52, v222, 50
	v_readlane_b32 s53, v222, 51
	v_readlane_b32 s54, v222, 52
	v_readlane_b32 s55, v222, 53
	v_readlane_b32 s56, v222, 54
	v_readlane_b32 s57, v222, 55
	v_readlane_b32 s58, v222, 56
	v_readlane_b32 s59, v222, 57
	v_readlane_b32 s60, v222, 58
	v_readlane_b32 s61, v222, 59
	v_readlane_b32 s62, v222, 60
	v_readlane_b32 s63, v222, 61
	v_readlane_b32 s64, v222, 62
	v_readlane_b32 s65, v222, 63
	v_readlane_b32 s66, v223, 0
	v_readlane_b32 s67, v223, 1
	v_readlane_b32 s68, v223, 2
	v_readlane_b32 s69, v223, 3
	v_readlane_b32 s70, v223, 4
	v_readlane_b32 s71, v223, 5
	v_readlane_b32 s72, v223, 6
	v_readlane_b32 s73, v223, 7
	v_readlane_b32 s74, v223, 8
	v_readlane_b32 s75, v223, 9
	v_readlane_b32 s76, v223, 10
	v_readlane_b32 s77, v223, 11
	v_readlane_b32 s78, v223, 12
	v_readlane_b32 s79, v223, 13
	v_readlane_b32 s80, v223, 14
	v_readlane_b32 s81, v223, 15
	v_readlane_b32 s82, v223, 16
	v_readlane_b32 s83, v223, 17
	v_readlane_b32 s84, v223, 18
	v_readlane_b32 s85, v223, 19
	v_readlane_b32 s86, v223, 20
	v_readlane_b32 s87, v223, 21
	s_nop 1

; __global__ void __launch_bounds__(NTHREADS, 2) fwd(Args args) {
	.amdhsa_kernel _Z3fwd4Args
		.amdhsa_group_segment_fixed_size 0
		.amdhsa_private_segment_fixed_size 0
		.amdhsa_kernarg_size 432
		.amdhsa_user_sgpr_count 2
		.amdhsa_user_sgpr_dispatch_ptr 0
		.amdhsa_user_sgpr_queue_ptr 0
		.amdhsa_user_sgpr_kernarg_segment_ptr 1
		.amdhsa_user_sgpr_dispatch_id 0
		.amdhsa_user_sgpr_kernarg_preload_length 0
		.amdhsa_user_sgpr_kernarg_preload_offset 0
		.amdhsa_user_sgpr_private_segment_size 0
		.amdhsa_uses_dynamic_stack 0
		.amdhsa_enable_private_segment 0
		.amdhsa_system_sgpr_workgroup_id_x 1
		.amdhsa_system_sgpr_workgroup_id_y 0
		.amdhsa_system_sgpr_workgroup_id_z 0
		.amdhsa_system_sgpr_workgroup_info 0
		.amdhsa_system_vgpr_workitem_id 0
		.amdhsa_next_free_vgpr 224
		.amdhsa_next_free_sgpr 100
		.amdhsa_accum_offset 224
		.amdhsa_reserve_vcc 1
		.amdhsa_float_round_mode_32 0
		.amdhsa_float_round_mode_16_64 0
		.amdhsa_float_denorm_mode_32 3
		.amdhsa_float_denorm_mode_16_64 3
		.amdhsa_dx10_clamp 1
		.amdhsa_ieee_mode 1
		.amdhsa_fp16_overflow 0
		.amdhsa_tg_split 0
		.amdhsa_exception_fp_ieee_invalid_op 0
		.amdhsa_exception_fp_denorm_src 0
		.amdhsa_exception_fp_ieee_div_zero 0
		.amdhsa_exception_fp_ieee_overflow 0
		.amdhsa_exception_fp_ieee_underflow 0
		.amdhsa_exception_fp_ieee_inexact 0
		.amdhsa_exception_int_div_zero 0
	.end_amdhsa_kernel

; __global__ void __launch_bounds__(NTHREADS, 2) fwd(Args args) {
amdhsa.kernels:
  - .agpr_count:     0
    .args:
      - .offset:         0
        .size:           176
        .value_kind:     by_value
      - .offset:         176
        .size:           4
        .value_kind:     hidden_block_count_x
      - .offset:         180
        .size:           4
        .value_kind:     hidden_block_count_y
      - .offset:         184
        .size:           4
        .value_kind:     hidden_block_count_z
      - .offset:         188
        .size:           2
        .value_kind:     hidden_group_size_x
      - .offset:         190
        .size:           2
        .value_kind:     hidden_group_size_y
      - .offset:         192
        .size:           2
        .value_kind:     hidden_group_size_z
      - .offset:         194
        .size:           2
        .value_kind:     hidden_remainder_x
      - .offset:         196
        .size:           2
        .value_kind:     hidden_remainder_y
      - .offset:         198
        .size:           2
        .value_kind:     hidden_remainder_z
      - .offset:         216
        .size:           8
        .value_kind:     hidden_global_offset_x
      - .offset:         224
        .size:           8
        .value_kind:     hidden_global_offset_y
      - .offset:         232
        .size:           8
        .value_kind:     hidden_global_offset_z
      - .offset:         240
        .size:           2
        .value_kind:     hidden_grid_dims
      - .offset:         296
        .size:           4
        .value_kind:     hidden_dynamic_lds_size
    .group_segment_fixed_size: 0
    .kernarg_segment_align: 8
    .kernarg_segment_size: 432
    .language:       OpenCL C
    .language_version:
      - 2
      - 0
    .max_flat_workgroup_size: 512
    .name:           _Z3fwd4Args
    .private_segment_fixed_size: 0
    .sgpr_count:     106
    .sgpr_spill_count: 114
    .symbol:         _Z3fwd4Args.kd
    .uniform_work_group_size: 1
    .uses_dynamic_stack: false
    .vgpr_count:     224
    .vgpr_spill_count: 0
    .wavefront_size: 64
